# in-proj GEMM: next tile's phase-1 LDS-DMA issued before the epilogue stores; tiles>=1 run a peeled first K-iteration whose phase-4 wait is vmcnt(22), so it no longer waits for the 16 stores
# speedup vs baseline: 1.0046x; 1.0002x over previous
; #define PG8_STAGE(bufoff, gbase, voff) do { _Pragma("unroll") for (int _i = 0; _i < 2; ++_i) \
;         __builtin_amdgcn_global_load_lds((const unsigned*)((const char*)(gbase) + (voff)[_i]), (LAS unsigned*)(lds + (bufoff) + ldsw + _i * 8192), 16, 0, 0); } while (0)
; #define PG8_WAIT_V(n) asm volatile("s_waitcnt vmcnt(" #n ")" ::: "memory")
; #define PG8_BAR __builtin_amdgcn_s_barrier()
; template <class Epi>
; DI void gemm_phase(LAS unsigned char* lds, const Gemm g, const StaticOrder& S, const Epi& E, const int tid) {
;     ...
;     for (int i = 0; i < 2; ++i) { int R, C; stage_rc(tid * 16 + i * 8192, R, C); const int Rb = Epi::PERM ? ((R & ~31) + perm32(R & 31)) : R;
;         voffA[i] = g.ant ? (unsigned)((((R >> 4) & 3) << 14) | (((R >> 6) & 1) << 12) | (((C >> 5) & 1) << 10) | (((C >> 3) & 3) << 8) | ((R & 15) << 4)) : (unsigned)(R * lda + C) * 2u;
;         voffB[i] = (unsigned)(Rb * K + C) * 2u; }
;     const size_t kstep = (size_t)(BK * 2);
;     const size_t hstepA = g.ant ? (size_t)65536 : (size_t)HALF * lda * 2, hstepB = (size_t)HALF * K * 2;
;     const size_t tstepA = g.ant ? (size_t)g.ant * 131072 : 2 * hstepA, tstepB = 2 * hstepB;
;     ...
;     const unsigned ldsw = (unsigned)wid * 1024u;
;     const int aoff = lds_byte(wr * 64 + fr, fq * 8), boff = lds_byte(wc * 32 + fr, fq * 8);
;     ...
;     Unit cur, nxt; int ui = 0;
;     if (!S.next(0, cur)) return;
;     f32x4 acc[2][2][4][2];
; #pragma unroll
;     for (int a = 0; a < 2; ++a)
; #pragma unroll
;         for (int b = 0; b < 2; ++b)
; #pragma unroll
;             for (int m = 0; m < 4; ++m)
; #pragma unroll
;                 for (int n = 0; n < 2; ++n) acc[a][b][m][n] = (f32x4){0.f, 0.f, 0.f, 0.f};
;     bf16x8 At[4][2], B0[2][2], B1[2][2];
;     const char* cA = (const char*)g.A + (size_t)cur.pm * tstepA; const char* cB = (const char*)g.Bt + (size_t)cur.pn * tstepB;
;     PG8_STAGE(PG8_SB(0, 0), cB, voffB); PG8_STAGE(PG8_SA(0, 0), cA, voffA); PG8_STAGE(PG8_SB(0, 1), cB + hstepB, voffB); PG8_STAGE(PG8_SA(0, 1), cA + hstepA, voffA);
;     if (wr == 1) PG8_BAR;
;     PG8_WAIT_V(4); PG8_BAR;
;     PG8_STAGE(PG8_SB(1, 0), cB + kstep, voffB); PG8_STAGE(PG8_SA(1, 0), cA + PG8_KTA(1), voffA); PG8_STAGE(PG8_SB(1, 1), cB + hstepB + kstep, voffB);
;     PG8_WAIT_V(6); PG8_BAR;
.LBB0_58:
	s_and_b32 s30, s8, 3
	s_add_i32 m0, s41, 0x18000
	v_lshl_add_u64 v[8:9], v[8:9], 0, s[84:85]
	s_lshr_b32 s58, s24, 8
	s_lshl_b32 s31, s7, 13
	s_lshl_b32 s34, s30, 12
	s_waitcnt vmcnt(4)
	s_barrier
	global_load_lds_dwordx4 v[8:9], off
	v_lshl_add_u64 v[6:7], v[6:7], 0, s[84:85]
	s_add_i32 m0, s41, 0x1a000
	s_add_i32 s59, s41, 0x8000
	s_add_i32 s60, s41, 0xa000
	global_load_lds_dwordx4 v[6:7], off
	v_lshl_add_u64 v[4:5], v[4:5], 0, s[84:85]
	s_mov_b32 m0, s59
	s_add_u32 s8, s4, 0x80080
	global_load_lds_dwordx4 v[4:5], off
	v_lshl_add_u64 v[2:3], v[2:3], 0, s[84:85]
	s_mov_b32 m0, s60
	s_addc_u32 s9, s5, 0
	global_load_lds_dwordx4 v[2:3], off
	s_add_i32 m0, s41, 0x1c000
	v_lshl_add_u64 v[2:3], s[8:9], 0, v[0:1]
	global_load_lds_dwordx4 v[2:3], off
	v_lshl_add_u64 v[2:3], s[8:9], 0, v[130:131]
	s_add_i32 m0, s41, 0x1e000
	s_sext_i32_i16 s63, s6
	global_load_lds_dwordx4 v[2:3], off
	s_lshl_b32 s6, s7, 12
	s_lshl_b32 s7, s30, 10
	v_bfe_u32 v2, v148, 4, 2
	v_lshlrev_b32_e32 v3, 6, v149
	v_lshlrev_b32_e32 v4, 2, v149
	s_or_b32 s6, s7, s6
	v_lshl_or_b32 v3, v2, 4, v3
	v_and_b32_e32 v4, 32, v4
	s_ashr_i32 s7, s6, 31
	s_ashr_i32 s61, s10, 31
	v_bitop3_b32 v5, s31, v3, v4 bitop3:0xf6
	v_bitop3_b32 v150, s34, v3, v4 bitop3:0xf6
	v_lshlrev_b32_e32 v3, 4, v149
	s_add_u32 s6, s82, s6
	v_lshl_or_b32 v2, v2, 8, v3
	v_mov_b32_e32 v3, v1
	s_addc_u32 s7, s83, s7
	v_lshl_add_u64 v[136:137], s[6:7], 0, v[2:3]
	v_lshlrev_b32_e32 v2, 15, v14
	v_and_b32_e32 v2, 0xffff0000, v2
	v_lshl_add_u32 v2, v13, 12, v2
	v_and_b32_e32 v3, 1, v14
	v_lshl_or_b32 v2, v3, 6, v2
	v_lshl_add_u32 v138, v15, 1, v2
	v_lshlrev_b32_e32 v2, 15, v10
	v_and_b32_e32 v2, 0xffff0000, v2
	s_waitcnt vmcnt(6)
	v_lshl_add_u32 v2, v11, 12, v2
	v_and_b32_e32 v3, 1, v10
	v_lshl_or_b32 v2, v3, 6, v2
	v_mov_b32_e32 v139, v1
	v_lshl_add_u32 v140, v12, 1, v2
	v_mov_b32_e32 v141, v1
	s_mov_b32 s62, 0
	v_mov_b64_e32 v[142:143], s[78:79]
	v_add_u32_e32 v151, 0, v5
	s_barrier
	s_mov_b32 s101, 0

; #define PG8_STAGE(bufoff, gbase, voff) do { _Pragma("unroll") for (int _i = 0; _i < 2; ++_i) \
;         __builtin_amdgcn_global_load_lds((const unsigned*)((const char*)(gbase) + (voff)[_i]), (LAS unsigned*)(lds + (bufoff) + ldsw + _i * 8192), 16, 0, 0); } while (0)
; #define PG8_LDA(dst, b, h) do { _Pragma("unroll") for (int m = 0; m < 4; ++m) _Pragma("unroll") for (int k = 0; k < 2; ++k) dst[m][k] = *(const LAS bf16x8*)(lds + PG8_SA(b, h) + aoff + m * 2048 + k * 1024); } while (0)
; #define PG8_LDB(dst, b, h) do { _Pragma("unroll") for (int n = 0; n < 2; ++n) _Pragma("unroll") for (int k = 0; k < 2; ++k) dst[n][k] = *(const LAS bf16x8*)(lds + PG8_SB(b, h) + boff + n * 2048 + k * 1024); } while (0)
; #define PG8_MMA(ai, bj, At, Bt) do { __builtin_amdgcn_s_setprio(1); _Pragma("unroll") for (int m = 0; m < 4; ++m) _Pragma("unroll") for (int n = 0; n < 2; ++n) _Pragma("unroll") for (int k = 0; k < 2; ++k) \
;         acc[ai][bj][m][n] = __builtin_amdgcn_mfma_f32_16x16x32_bf16(Bt[n][k], At[m][k], acc[ai][bj][m][n], 0, 0, 0); __builtin_amdgcn_s_setprio(0); } while (0)
; #define PG8_WAIT_L(n) asm volatile("s_waitcnt lgkmcnt(" #n ")" ::: "memory")
; #define PG8_BAR __builtin_amdgcn_s_barrier()
; #define PG8_SCHED __builtin_amdgcn_sched_barrier(0)
; template <class Epi>
; DI void gemm_phase(LAS unsigned char* lds, const Gemm g, const StaticOrder& S, const Epi& E, const int tid) {
;     ...
;         const bool has_next = S.next(ui + 1, nxt);
;         const char* nA = has_next ? (const char*)g.A + (size_t)nxt.pm * tstepA : cA; const char* nB = has_next ? (const char*)g.Bt + (size_t)nxt.pn * tstepB : cB;
;         for (int t = 0; t < nt; t += 2) {
;             const bool last = (t == nt - 2);
;             const char* a1 = cA + PG8_KTA(t + 1);
;             const char* a2 = last ? nA : cA + PG8_KTA(t + 2); const char* b2 = last ? nB : cB + (size_t)(t + 2) * kstep;
;             const char* a3 = last ? nA + PG8_KTA(1) : cA + PG8_KTA(t + 3); const char* b3 = b2 + kstep;
;             PG8_LDB(B0, 0, 0); PG8_SCHED; PG8_LDA(At, 0, 0); PG8_STAGE(PG8_SA(1, 1), a1 + hstepA, voffA);
;             PG8_WAIT_L(8); PG8_BAR; PG8_WAIT_L(0); PG8_MMA(0, 0, At, B0); PG8_BAR; PG8_SCHED;
.LBB0_61:
	s_ashr_i32 s43, s42, 31
	v_cmp_lt_i64_e32 vcc, s[6:7], v[142:143]
	s_lshl_b64 s[6:7], s[42:43], 20
	s_add_u32 s46, s70, s6
	s_addc_u32 s47, s71, s7
	s_and_b64 s[6:7], vcc, exec
	s_cselect_b32 s30, s47, s45
	s_cselect_b32 s31, s46, s44
	s_ashr_i32 s39, s38, 31
	s_lshl_b64 s[6:7], s[38:39], 20
	s_add_u32 s48, s36, s6
	s_addc_u32 s49, s37, s7
	s_and_b64 s[6:7], vcc, exec
	s_cselect_b32 s39, s49, s5
	s_cselect_b32 s43, s48, s4
	s_add_u32 s64, s31, 0x80
	s_addc_u32 s65, s30, 0
	s_add_u32 s6, s44, 0x80080
	s_addc_u32 s7, s45, 0
	s_add_u32 s66, s4, 0x100
	v_mov_b64_e32 v[2:3], 0
	s_addc_u32 s67, s5, 0
	s_mov_b32 s68, -2
	s_mov_b64 s[4:5], 0
	v_mov_b64_e32 v[4:5], 0
	v_mov_b64_e32 v[6:7], 0
	v_mov_b64_e32 v[8:9], 0
	v_mov_b64_e32 v[10:11], 0
	v_mov_b64_e32 v[12:13], 0
	v_mov_b64_e32 v[14:15], 0
	v_mov_b64_e32 v[16:17], 0
	v_mov_b64_e32 v[18:19], 0
	v_mov_b64_e32 v[20:21], 0
	v_mov_b64_e32 v[22:23], 0
	v_mov_b64_e32 v[24:25], 0
	v_mov_b64_e32 v[26:27], 0
	v_mov_b64_e32 v[28:29], 0
	v_mov_b64_e32 v[30:31], 0
	v_mov_b64_e32 v[32:33], 0
	v_mov_b64_e32 v[34:35], 0
	v_mov_b64_e32 v[36:37], 0
	v_mov_b64_e32 v[38:39], 0
	v_mov_b64_e32 v[40:41], 0
	v_mov_b64_e32 v[42:43], 0
	v_mov_b64_e32 v[44:45], 0
	v_mov_b64_e32 v[46:47], 0
	v_mov_b64_e32 v[48:49], 0
	v_mov_b64_e32 v[50:51], 0
	v_mov_b64_e32 v[52:53], 0
	v_mov_b64_e32 v[54:55], 0
	v_mov_b64_e32 v[56:57], 0
	v_mov_b64_e32 v[58:59], 0
	v_mov_b64_e32 v[60:61], 0
	v_mov_b64_e32 v[62:63], 0
	v_mov_b64_e32 v[64:65], 0
	v_mov_b64_e32 v[66:67], 0
	v_mov_b64_e32 v[68:69], 0
	v_mov_b64_e32 v[70:71], 0
	v_mov_b64_e32 v[72:73], 0
	v_mov_b64_e32 v[74:75], 0
	v_mov_b64_e32 v[76:77], 0
	v_mov_b64_e32 v[78:79], 0
	v_mov_b64_e32 v[80:81], 0
	v_mov_b64_e32 v[82:83], 0
	v_mov_b64_e32 v[84:85], 0
	v_mov_b64_e32 v[86:87], 0
	v_mov_b64_e32 v[88:89], 0
	v_mov_b64_e32 v[90:91], 0
	v_mov_b64_e32 v[92:93], 0
	v_mov_b64_e32 v[94:95], 0
	v_mov_b64_e32 v[96:97], 0
	v_mov_b64_e32 v[98:99], 0
	v_mov_b64_e32 v[100:101], 0
	v_mov_b64_e32 v[102:103], 0
	v_mov_b64_e32 v[104:105], 0
	v_mov_b64_e32 v[106:107], 0
	v_mov_b64_e32 v[108:109], 0
	v_mov_b64_e32 v[110:111], 0
	v_mov_b64_e32 v[112:113], 0
	v_mov_b64_e32 v[114:115], 0
	v_mov_b64_e32 v[116:117], 0
	v_mov_b64_e32 v[118:119], 0
	v_mov_b64_e32 v[120:121], 0
	v_mov_b64_e32 v[122:123], 0
	v_mov_b64_e32 v[124:125], 0
	v_mov_b64_e32 v[126:127], 0
	v_mov_b64_e32 v[128:129], 0
	v_lshl_add_u64 v[144:145], s[6:7], 0, v[138:139]
	v_lshl_add_u64 v[146:147], s[6:7], 0, v[140:141]
	s_add_u32 s6, s44, s4
	s_addc_u32 s7, s45, s5
	s_add_u32 s8, s6, 0x100
	s_addc_u32 s9, s7, 0
	s_add_u32 s69, s66, s4
	s_addc_u32 s78, s67, s5
	s_add_u32 s86, s6, 0x180
	s_addc_u32 s87, s7, 0
	s_cmpk_eq_i32 s4, 0xf00
	s_cselect_b32 s51, s30, s9
	s_cselect_b32 s50, s31, s8
	s_cselect_b32 s7, s39, s78
	s_cselect_b32 s6, s43, s69
	s_cselect_b32 s9, s65, s87
	s_cselect_b32 s8, s64, s86
	s_add_u32 s86, s44, s4
	s_addc_u32 s87, s45, s5
	s_add_u32 s86, s86, 0x80080
	s_addc_u32 s87, s87, 0
	v_add_u32_e32 v241, 0x10000, v150
	v_add_u32_e32 v242, 0x14000, v150
	v_add_u32_e32 v243, 0x18000, v150
	v_add_u32_e32 v244, 0x1c000, v150
	s_cmp_eq_u32 s101, 0
	s_cbranch_scc1 .LBB0_62
	s_add_i32 s69, 0, 0x10000
	ds_read_b128 v[158:161], v241
	ds_read_b128 v[162:165], v241 offset:1024
	ds_read_b128 v[166:169], v241 offset:2048
	ds_read_b128 v[178:181], v241 offset:3072
	ds_read_b128 v[182:185], v151
	ds_read_b128 v[186:189], v151 offset:1024
	ds_read_b128 v[190:193], v151 offset:2048
	ds_read_b128 v[194:197], v151 offset:3072
	ds_read_b128 v[198:201], v151 offset:4096
	ds_read_b128 v[202:205], v151 offset:5120
	ds_read_b128 v[206:209], v151 offset:6144
	ds_read_b128 v[210:213], v151 offset:7168
	s_waitcnt lgkmcnt(8)
	s_barrier
	s_waitcnt lgkmcnt(0)
	s_setprio 1
	s_waitcnt lgkmcnt(0)
	v_mfma_f32_16x16x32_bf16 v[126:129], v[158:161], v[182:185], v[126:129]
	v_mfma_f32_16x16x32_bf16 v[122:125], v[166:169], v[182:185], v[122:125]
	v_mfma_f32_16x16x32_bf16 v[118:121], v[158:161], v[190:193], v[118:121]
	v_mfma_f32_16x16x32_bf16 v[114:117], v[166:169], v[190:193], v[114:117]
	v_mfma_f32_16x16x32_bf16 v[102:105], v[158:161], v[198:201], v[102:105]
	v_mfma_f32_16x16x32_bf16 v[98:101], v[166:169], v[198:201], v[98:101]
	v_mfma_f32_16x16x32_bf16 v[86:89], v[158:161], v[206:209], v[86:89]
	v_mfma_f32_16x16x32_bf16 v[82:85], v[166:169], v[206:209], v[82:85]
	v_mfma_f32_16x16x32_bf16 v[126:129], v[162:165], v[186:189], v[126:129]
	v_mfma_f32_16x16x32_bf16 v[122:125], v[178:181], v[186:189], v[122:125]
	v_mfma_f32_16x16x32_bf16 v[118:121], v[162:165], v[194:197], v[118:121]
	v_mfma_f32_16x16x32_bf16 v[114:117], v[178:181], v[194:197], v[114:117]
	v_mfma_f32_16x16x32_bf16 v[102:105], v[162:165], v[202:205], v[102:105]
	v_mfma_f32_16x16x32_bf16 v[98:101], v[178:181], v[202:205], v[98:101]
	v_mfma_f32_16x16x32_bf16 v[86:89], v[162:165], v[210:213], v[86:89]
	v_mfma_f32_16x16x32_bf16 v[82:85], v[178:181], v[210:213], v[82:85]
	s_setprio 0
	s_barrier
	s_add_i32 s78, 0, 0x14000
	s_add_i32 s69, s69, s26
	ds_read_b128 v[214:217], v242
	ds_read_b128 v[218:221], v242 offset:1024
	ds_read_b128 v[222:225], v242 offset:2048
	ds_read_b128 v[226:229], v242 offset:3072
	s_mov_b32 m0, s69
	s_nop 0
	global_load_lds_dwordx4 v0, s[6:7]
	s_add_i32 m0, s69, 0x2000
	s_nop 0
	global_load_lds_dwordx4 v130, s[6:7]
	s_barrier
; #define PG8_STAGE(bufoff, gbase, voff) do { _Pragma("unroll") for (int _i = 0; _i < 2; ++_i) \
;         __builtin_amdgcn_global_load_lds((const unsigned*)((const char*)(gbase) + (voff)[_i]), (LAS unsigned*)(lds + (bufoff) + ldsw + _i * 8192), 16, 0, 0); } while (0)
; #define PG8_LDA(dst, b, h) do { _Pragma("unroll") for (int m = 0; m < 4; ++m) _Pragma("unroll") for (int k = 0; k < 2; ++k) dst[m][k] = *(const LAS bf16x8*)(lds + PG8_SA(b, h) + aoff + m * 2048 + k * 1024); } while (0)
; #define PG8_LDB(dst, b, h) do { _Pragma("unroll") for (int n = 0; n < 2; ++n) _Pragma("unroll") for (int k = 0; k < 2; ++k) dst[n][k] = *(const LAS bf16x8*)(lds + PG8_SB(b, h) + boff + n * 2048 + k * 1024); } while (0)
; #define PG8_MMA(ai, bj, At, Bt) do { __builtin_amdgcn_s_setprio(1); _Pragma("unroll") for (int m = 0; m < 4; ++m) _Pragma("unroll") for (int n = 0; n < 2; ++n) _Pragma("unroll") for (int k = 0; k < 2; ++k) \
;         acc[ai][bj][m][n] = __builtin_amdgcn_mfma_f32_16x16x32_bf16(Bt[n][k], At[m][k], acc[ai][bj][m][n], 0, 0, 0); __builtin_amdgcn_s_setprio(0); } while (0)
; #define PG8_WAIT_V(n) asm volatile("s_waitcnt vmcnt(" #n ")" ::: "memory")
; #define PG8_WAIT_L(n) asm volatile("s_waitcnt lgkmcnt(" #n ")" ::: "memory")
; #define PG8_BAR __builtin_amdgcn_s_barrier()
; #define PG8_SCHED __builtin_amdgcn_sched_barrier(0)
; template <class Epi>
; DI void gemm_phase(LAS unsigned char* lds, const Gemm g, const StaticOrder& S, const Epi& E, const int tid) {
;     ...
;             PG8_WAIT_L(8); PG8_BAR; PG8_WAIT_L(0); PG8_MMA(0, 0, At, B0); PG8_BAR; PG8_SCHED;
;             PG8_LDB(B1, 0, 1); PG8_STAGE(PG8_SB(0, 0), b2, voffB);
;             PG8_BAR; PG8_WAIT_L(0); PG8_MMA(0, 1, At, B1); PG8_BAR;
;             PG8_LDA(At, 0, 1); PG8_STAGE(PG8_SA(0, 0), a2, voffA);
;             PG8_BAR; PG8_WAIT_L(0); PG8_MMA(1, 0, At, B0); PG8_BAR; PG8_SCHED;
;             PG8_STAGE(PG8_SB(0, 1), b2 + hstepB, voffB);
;             PG8_WAIT_V(6); PG8_BAR; PG8_MMA(1, 1, At, B1); PG8_BAR;
;             PG8_LDB(B0, 1, 0); PG8_SCHED; PG8_LDA(At, 1, 0); PG8_STAGE(PG8_SA(0, 1), a2 + hstepA, voffA);
;             PG8_WAIT_L(8); PG8_BAR; PG8_WAIT_L(0); PG8_MMA(0, 0, At, B0); PG8_BAR; PG8_SCHED;
	s_waitcnt lgkmcnt(0)
	s_setprio 1
	s_waitcnt lgkmcnt(0)
	v_mfma_f32_16x16x32_bf16 v[110:113], v[214:217], v[182:185], v[110:113]
	v_mfma_f32_16x16x32_bf16 v[106:109], v[222:225], v[182:185], v[106:109]
	v_mfma_f32_16x16x32_bf16 v[94:97], v[214:217], v[190:193], v[94:97]
	v_mfma_f32_16x16x32_bf16 v[90:93], v[222:225], v[190:193], v[90:93]
	v_mfma_f32_16x16x32_bf16 v[78:81], v[214:217], v[198:201], v[78:81]
	v_mfma_f32_16x16x32_bf16 v[74:77], v[222:225], v[198:201], v[74:77]
	v_mfma_f32_16x16x32_bf16 v[70:73], v[214:217], v[206:209], v[70:73]
	v_mfma_f32_16x16x32_bf16 v[66:69], v[222:225], v[206:209], v[66:69]
	v_mfma_f32_16x16x32_bf16 v[110:113], v[218:221], v[186:189], v[110:113]
	v_mfma_f32_16x16x32_bf16 v[106:109], v[226:229], v[186:189], v[106:109]
	v_mfma_f32_16x16x32_bf16 v[94:97], v[218:221], v[194:197], v[94:97]
	v_mfma_f32_16x16x32_bf16 v[90:93], v[226:229], v[194:197], v[90:93]
	v_mfma_f32_16x16x32_bf16 v[78:81], v[218:221], v[202:205], v[78:81]
	v_mfma_f32_16x16x32_bf16 v[74:77], v[226:229], v[202:205], v[74:77]
	v_mfma_f32_16x16x32_bf16 v[70:73], v[218:221], v[210:213], v[70:73]
	v_mfma_f32_16x16x32_bf16 v[66:69], v[226:229], v[210:213], v[66:69]
	s_setprio 0
	s_mov_b32 m0, s41
	s_barrier
	ds_read_b128 v[182:185], v151 offset:16384
	ds_read_b128 v[186:189], v151 offset:17408
	ds_read_b128 v[190:193], v151 offset:18432
	ds_read_b128 v[194:197], v151 offset:19456
	ds_read_b128 v[198:201], v151 offset:20480
	ds_read_b128 v[202:205], v151 offset:21504
	ds_read_b128 v[206:209], v151 offset:22528
	ds_read_b128 v[210:213], v151 offset:23552
	global_load_lds_dwordx4 v134, s[50:51]
	s_mov_b32 m0, s55
	s_nop 0
	global_load_lds_dwordx4 v132, s[50:51]
	s_barrier
	s_waitcnt lgkmcnt(0)
	s_setprio 1
	s_waitcnt lgkmcnt(0)
	v_mfma_f32_16x16x32_bf16 v[62:65], v[158:161], v[182:185], v[62:65]
	v_mfma_f32_16x16x32_bf16 v[58:61], v[166:169], v[182:185], v[58:61]
	v_mfma_f32_16x16x32_bf16 v[54:57], v[158:161], v[190:193], v[54:57]
	v_mfma_f32_16x16x32_bf16 v[50:53], v[166:169], v[190:193], v[50:53]
	v_mfma_f32_16x16x32_bf16 v[38:41], v[158:161], v[198:201], v[38:41]
	v_mfma_f32_16x16x32_bf16 v[34:37], v[166:169], v[198:201], v[34:37]
	v_mfma_f32_16x16x32_bf16 v[22:25], v[158:161], v[206:209], v[22:25]
	v_mfma_f32_16x16x32_bf16 v[18:21], v[166:169], v[206:209], v[18:21]
	v_mfma_f32_16x16x32_bf16 v[62:65], v[162:165], v[186:189], v[62:65]
	v_mfma_f32_16x16x32_bf16 v[58:61], v[178:181], v[186:189], v[58:61]
	v_mfma_f32_16x16x32_bf16 v[54:57], v[162:165], v[194:197], v[54:57]
	v_mfma_f32_16x16x32_bf16 v[50:53], v[178:181], v[194:197], v[50:53]
	v_mfma_f32_16x16x32_bf16 v[38:41], v[162:165], v[202:205], v[38:41]
	v_mfma_f32_16x16x32_bf16 v[34:37], v[178:181], v[202:205], v[34:37]
	v_mfma_f32_16x16x32_bf16 v[22:25], v[162:165], v[210:213], v[22:25]
	v_mfma_f32_16x16x32_bf16 v[18:21], v[178:181], v[210:213], v[18:21]
	s_setprio 0
	s_barrier
	s_add_u32 s86, s6, 0x80000
	s_addc_u32 s87, s7, 0
	s_add_i32 s69, s78, s26
	s_mov_b32 m0, s69
	s_nop 0
	global_load_lds_dwordx4 v0, s[86:87]
	s_add_i32 m0, s69, 0x2000
	s_nop 0
	global_load_lds_dwordx4 v130, s[86:87]
	s_waitcnt vmcnt(22)
	s_barrier
	s_setprio 1
	v_mfma_f32_16x16x32_bf16 v[46:49], v[214:217], v[182:185], v[46:49]
	v_mfma_f32_16x16x32_bf16 v[42:45], v[222:225], v[182:185], v[42:45]
	v_mfma_f32_16x16x32_bf16 v[30:33], v[214:217], v[190:193], v[30:33]
	v_mfma_f32_16x16x32_bf16 v[26:29], v[222:225], v[190:193], v[26:29]
	v_mfma_f32_16x16x32_bf16 v[14:17], v[214:217], v[198:201], v[14:17]
	v_mfma_f32_16x16x32_bf16 v[10:13], v[222:225], v[198:201], v[10:13]
	v_mfma_f32_16x16x32_bf16 v[6:9], v[214:217], v[206:209], v[6:9]
	v_mfma_f32_16x16x32_bf16 v[2:5], v[222:225], v[206:209], v[2:5]
	v_mfma_f32_16x16x32_bf16 v[46:49], v[218:221], v[186:189], v[46:49]
	v_mfma_f32_16x16x32_bf16 v[42:45], v[226:229], v[186:189], v[42:45]
	v_mfma_f32_16x16x32_bf16 v[30:33], v[218:221], v[194:197], v[30:33]
	v_mfma_f32_16x16x32_bf16 v[26:29], v[226:229], v[194:197], v[26:29]
	v_mfma_f32_16x16x32_bf16 v[14:17], v[218:221], v[202:205], v[14:17]
	v_mfma_f32_16x16x32_bf16 v[10:13], v[226:229], v[202:205], v[10:13]
	v_mfma_f32_16x16x32_bf16 v[6:9], v[218:221], v[210:213], v[6:9]
	v_mfma_f32_16x16x32_bf16 v[2:5], v[226:229], v[210:213], v[2:5]
	s_setprio 0
	s_add_i32 s69, 0, 0x18000
	s_barrier
	ds_read_b128 v[158:161], v243
	ds_read_b128 v[162:165], v243 offset:1024
	ds_read_b128 v[166:169], v243 offset:2048
	ds_read_b128 v[178:181], v243 offset:3072
	s_add_u32 s50, s50, 0x80000
	s_addc_u32 s51, s51, 0
	s_mov_b32 m0, s56
	s_nop 0
	ds_read_b128 v[182:185], v151 offset:32768
	ds_read_b128 v[186:189], v151 offset:33792
	ds_read_b128 v[190:193], v151 offset:34816
	ds_read_b128 v[194:197], v151 offset:35840
	ds_read_b128 v[198:201], v151 offset:36864
	ds_read_b128 v[202:205], v151 offset:37888
	ds_read_b128 v[206:209], v151 offset:38912
	ds_read_b128 v[210:213], v151 offset:39936
	global_load_lds_dwordx4 v134, s[50:51]
	s_mov_b32 m0, s57
	s_nop 0
	global_load_lds_dwordx4 v132, s[50:51]
	s_waitcnt lgkmcnt(8)
	s_barrier
	s_waitcnt lgkmcnt(0)
	s_setprio 1
	s_waitcnt lgkmcnt(0)
	v_mfma_f32_16x16x32_bf16 v[126:129], v[158:161], v[182:185], v[126:129]
	v_mfma_f32_16x16x32_bf16 v[122:125], v[166:169], v[182:185], v[122:125]
	v_mfma_f32_16x16x32_bf16 v[118:121], v[158:161], v[190:193], v[118:121]
	v_mfma_f32_16x16x32_bf16 v[114:117], v[166:169], v[190:193], v[114:117]
	v_mfma_f32_16x16x32_bf16 v[102:105], v[158:161], v[198:201], v[102:105]
	v_mfma_f32_16x16x32_bf16 v[98:101], v[166:169], v[198:201], v[98:101]
	v_mfma_f32_16x16x32_bf16 v[86:89], v[158:161], v[206:209], v[86:89]
	v_mfma_f32_16x16x32_bf16 v[82:85], v[166:169], v[206:209], v[82:85]
	v_mfma_f32_16x16x32_bf16 v[126:129], v[162:165], v[186:189], v[126:129]
	v_mfma_f32_16x16x32_bf16 v[122:125], v[178:181], v[186:189], v[122:125]
	v_mfma_f32_16x16x32_bf16 v[118:121], v[162:165], v[194:197], v[118:121]
	v_mfma_f32_16x16x32_bf16 v[114:117], v[178:181], v[194:197], v[114:117]
	v_mfma_f32_16x16x32_bf16 v[102:105], v[162:165], v[202:205], v[102:105]
	v_mfma_f32_16x16x32_bf16 v[98:101], v[178:181], v[202:205], v[98:101]
	v_mfma_f32_16x16x32_bf16 v[86:89], v[162:165], v[210:213], v[86:89]
	v_mfma_f32_16x16x32_bf16 v[82:85], v[178:181], v[210:213], v[82:85]
	s_setprio 0
	s_barrier
; #define PG8_STAGE(bufoff, gbase, voff) do { _Pragma("unroll") for (int _i = 0; _i < 2; ++_i) \
;         __builtin_amdgcn_global_load_lds((const unsigned*)((const char*)(gbase) + (voff)[_i]), (LAS unsigned*)(lds + (bufoff) + ldsw + _i * 8192), 16, 0, 0); } while (0)
; #define PG8_LDA(dst, b, h) do { _Pragma("unroll") for (int m = 0; m < 4; ++m) _Pragma("unroll") for (int k = 0; k < 2; ++k) dst[m][k] = *(const LAS bf16x8*)(lds + PG8_SA(b, h) + aoff + m * 2048 + k * 1024); } while (0)
; #define PG8_LDB(dst, b, h) do { _Pragma("unroll") for (int n = 0; n < 2; ++n) _Pragma("unroll") for (int k = 0; k < 2; ++k) dst[n][k] = *(const LAS bf16x8*)(lds + PG8_SB(b, h) + boff + n * 2048 + k * 1024); } while (0)
; #define PG8_MMA(ai, bj, At, Bt) do { __builtin_amdgcn_s_setprio(1); _Pragma("unroll") for (int m = 0; m < 4; ++m) _Pragma("unroll") for (int n = 0; n < 2; ++n) _Pragma("unroll") for (int k = 0; k < 2; ++k) \
;         acc[ai][bj][m][n] = __builtin_amdgcn_mfma_f32_16x16x32_bf16(Bt[n][k], At[m][k], acc[ai][bj][m][n], 0, 0, 0); __builtin_amdgcn_s_setprio(0); } while (0)
; #define PG8_WAIT_V(n) asm volatile("s_waitcnt vmcnt(" #n ")" ::: "memory")
; #define PG8_WAIT_L(n) asm volatile("s_waitcnt lgkmcnt(" #n ")" ::: "memory")
; #define PG8_BAR __builtin_amdgcn_s_barrier()
; #define PG8_SCHED __builtin_amdgcn_sched_barrier(0)
; template <class Epi>
; DI void gemm_phase(LAS unsigned char* lds, const Gemm g, const StaticOrder& S, const Epi& E, const int tid) {
;     ...
;             const bool last = (t == nt - 2);
;             const char* a1 = cA + PG8_KTA(t + 1);
;             const char* a2 = last ? nA : cA + PG8_KTA(t + 2); const char* b2 = last ? nB : cB + (size_t)(t + 2) * kstep;
;             const char* a3 = last ? nA + PG8_KTA(1) : cA + PG8_KTA(t + 3); const char* b3 = b2 + kstep;
;     ...
;             PG8_LDB(B1, 1, 1); PG8_STAGE(PG8_SB(1, 0), b3, voffB);
;             PG8_BAR; PG8_WAIT_L(0); PG8_MMA(0, 1, At, B1); PG8_BAR;
;             PG8_LDA(At, 1, 1); PG8_STAGE(PG8_SA(1, 0), a3, voffA);
;             PG8_BAR; PG8_WAIT_L(0); PG8_MMA(1, 0, At, B0); PG8_BAR; PG8_SCHED;
;             PG8_STAGE(PG8_SB(1, 1), b3 + hstepB, voffB);
;             PG8_WAIT_V(6); PG8_BAR; PG8_MMA(1, 1, At, B1); PG8_BAR;
	s_add_i32 s50, 0, 0x1c000
	s_add_i32 s51, s69, s26
	s_add_u32 s86, s6, s84
	s_addc_u32 s87, s7, s85
	s_mov_b32 m0, s51
	ds_read_b128 v[214:217], v244
	ds_read_b128 v[218:221], v244 offset:1024
	ds_read_b128 v[222:225], v244 offset:2048
	ds_read_b128 v[226:229], v244 offset:3072
	global_load_lds_dwordx4 v0, s[86:87]
	s_add_i32 m0, s51, 0x2000
	s_nop 0
	global_load_lds_dwordx4 v130, s[86:87]
	s_barrier
	s_waitcnt lgkmcnt(0)
	s_setprio 1
	s_waitcnt lgkmcnt(0)
	v_mfma_f32_16x16x32_bf16 v[110:113], v[214:217], v[182:185], v[110:113]
	v_mfma_f32_16x16x32_bf16 v[106:109], v[222:225], v[182:185], v[106:109]
	v_mfma_f32_16x16x32_bf16 v[94:97], v[214:217], v[190:193], v[94:97]
	v_mfma_f32_16x16x32_bf16 v[90:93], v[222:225], v[190:193], v[90:93]
	v_mfma_f32_16x16x32_bf16 v[78:81], v[214:217], v[198:201], v[78:81]
	v_mfma_f32_16x16x32_bf16 v[74:77], v[222:225], v[198:201], v[74:77]
	v_mfma_f32_16x16x32_bf16 v[70:73], v[214:217], v[206:209], v[70:73]
	v_mfma_f32_16x16x32_bf16 v[66:69], v[222:225], v[206:209], v[66:69]
	v_mfma_f32_16x16x32_bf16 v[110:113], v[218:221], v[186:189], v[110:113]
	v_mfma_f32_16x16x32_bf16 v[106:109], v[226:229], v[186:189], v[106:109]
	v_mfma_f32_16x16x32_bf16 v[94:97], v[218:221], v[194:197], v[94:97]
	v_mfma_f32_16x16x32_bf16 v[90:93], v[226:229], v[194:197], v[90:93]
	v_mfma_f32_16x16x32_bf16 v[78:81], v[218:221], v[202:205], v[78:81]
	v_mfma_f32_16x16x32_bf16 v[74:77], v[226:229], v[202:205], v[74:77]
	v_mfma_f32_16x16x32_bf16 v[70:73], v[218:221], v[210:213], v[70:73]
	v_mfma_f32_16x16x32_bf16 v[66:69], v[226:229], v[210:213], v[66:69]
	s_setprio 0
	s_mov_b32 m0, s59
	s_nop 0
	s_barrier
	ds_read_b128 v[182:185], v151 offset:49152
	ds_read_b128 v[186:189], v151 offset:50176
	ds_read_b128 v[190:193], v151 offset:51200
	ds_read_b128 v[194:197], v151 offset:52224
	ds_read_b128 v[198:201], v151 offset:53248
	ds_read_b128 v[202:205], v151 offset:54272
	ds_read_b128 v[206:209], v151 offset:55296
	ds_read_b128 v[210:213], v151 offset:56320
	global_load_lds_dwordx4 v134, s[8:9]
	s_mov_b32 m0, s60
	s_nop 0
	global_load_lds_dwordx4 v132, s[8:9]
	s_barrier
	s_waitcnt lgkmcnt(0)
	s_setprio 1
	s_waitcnt lgkmcnt(0)
	v_mfma_f32_16x16x32_bf16 v[62:65], v[158:161], v[182:185], v[62:65]
	v_mfma_f32_16x16x32_bf16 v[58:61], v[166:169], v[182:185], v[58:61]
	v_mfma_f32_16x16x32_bf16 v[54:57], v[158:161], v[190:193], v[54:57]
	v_mfma_f32_16x16x32_bf16 v[50:53], v[166:169], v[190:193], v[50:53]
	v_mfma_f32_16x16x32_bf16 v[38:41], v[158:161], v[198:201], v[38:41]
	v_mfma_f32_16x16x32_bf16 v[34:37], v[166:169], v[198:201], v[34:37]
	v_mfma_f32_16x16x32_bf16 v[22:25], v[158:161], v[206:209], v[22:25]
	v_mfma_f32_16x16x32_bf16 v[18:21], v[166:169], v[206:209], v[18:21]
	v_mfma_f32_16x16x32_bf16 v[62:65], v[162:165], v[186:189], v[62:65]
	v_mfma_f32_16x16x32_bf16 v[58:61], v[178:181], v[186:189], v[58:61]
	v_mfma_f32_16x16x32_bf16 v[54:57], v[162:165], v[194:197], v[54:57]
	v_mfma_f32_16x16x32_bf16 v[50:53], v[178:181], v[194:197], v[50:53]
	v_mfma_f32_16x16x32_bf16 v[38:41], v[162:165], v[202:205], v[38:41]
	v_mfma_f32_16x16x32_bf16 v[34:37], v[178:181], v[202:205], v[34:37]
	v_mfma_f32_16x16x32_bf16 v[22:25], v[162:165], v[210:213], v[22:25]
	v_mfma_f32_16x16x32_bf16 v[18:21], v[178:181], v[210:213], v[18:21]
	s_setprio 0
	s_barrier
	s_add_u32 s6, s6, 0x80080
	s_addc_u32 s7, s7, 0
	s_add_i32 s8, s50, s26
	s_mov_b32 m0, s8
	s_nop 0
	global_load_lds_dwordx4 v0, s[6:7]
	s_add_i32 m0, s8, 0x2000
	s_nop 0
	global_load_lds_dwordx4 v130, s[6:7]
	s_waitcnt vmcnt(6)
	s_barrier
	s_setprio 1
	v_mfma_f32_16x16x32_bf16 v[46:49], v[214:217], v[182:185], v[46:49]
	v_mfma_f32_16x16x32_bf16 v[42:45], v[222:225], v[182:185], v[42:45]
	v_mfma_f32_16x16x32_bf16 v[30:33], v[214:217], v[190:193], v[30:33]
	v_mfma_f32_16x16x32_bf16 v[26:29], v[222:225], v[190:193], v[26:29]
	v_mfma_f32_16x16x32_bf16 v[14:17], v[214:217], v[198:201], v[14:17]
	v_mfma_f32_16x16x32_bf16 v[10:13], v[222:225], v[198:201], v[10:13]
	v_mfma_f32_16x16x32_bf16 v[6:9], v[214:217], v[206:209], v[6:9]
	v_mfma_f32_16x16x32_bf16 v[2:5], v[222:225], v[206:209], v[2:5]
	v_mfma_f32_16x16x32_bf16 v[46:49], v[218:221], v[186:189], v[46:49]
	v_mfma_f32_16x16x32_bf16 v[42:45], v[226:229], v[186:189], v[42:45]
	v_mfma_f32_16x16x32_bf16 v[30:33], v[218:221], v[194:197], v[30:33]
	v_mfma_f32_16x16x32_bf16 v[26:29], v[226:229], v[194:197], v[26:29]
	v_mfma_f32_16x16x32_bf16 v[14:17], v[218:221], v[202:205], v[14:17]
	v_mfma_f32_16x16x32_bf16 v[10:13], v[226:229], v[202:205], v[10:13]
	v_mfma_f32_16x16x32_bf16 v[6:9], v[218:221], v[210:213], v[6:9]
	v_mfma_f32_16x16x32_bf16 v[2:5], v[226:229], v[210:213], v[2:5]
	s_setprio 0
	s_add_i32 s68, s68, 2
	s_add_u32 s4, s4, 0x100
	s_addc_u32 s5, s5, 0
	s_add_u32 s6, s44, s4
	s_addc_u32 s7, s45, s5
	s_add_u32 s8, s6, 0x100
	s_addc_u32 s9, s7, 0
	s_add_u32 s69, s66, s4
	s_addc_u32 s78, s67, s5
	s_add_u32 s86, s6, 0x180
	s_addc_u32 s87, s7, 0
	s_cmpk_eq_i32 s4, 0xf00
	s_cselect_b32 s51, s30, s9
	s_cselect_b32 s50, s31, s8
	s_cselect_b32 s7, s39, s78
	s_cselect_b32 s6, s43, s69
	s_cselect_b32 s9, s65, s87
	s_cselect_b32 s8, s64, s86
	s_add_u32 s86, s44, s4
	s_addc_u32 s87, s45, s5
	s_add_u32 s86, s86, 0x80080
	s_addc_u32 s87, s87, 0
	s_cmp_gt_u32 s68, 29
	s_barrier
	.p2align 6
; #define PG8_STAGE(bufoff, gbase, voff) do { _Pragma("unroll") for (int _i = 0; _i < 2; ++_i) \
;         __builtin_amdgcn_global_load_lds((const unsigned*)((const char*)(gbase) + (voff)[_i]), (LAS unsigned*)(lds + (bufoff) + ldsw + _i * 8192), 16, 0, 0); } while (0)
; #define PG8_LDA(dst, b, h) do { _Pragma("unroll") for (int m = 0; m < 4; ++m) _Pragma("unroll") for (int k = 0; k < 2; ++k) dst[m][k] = *(const LAS bf16x8*)(lds + PG8_SA(b, h) + aoff + m * 2048 + k * 1024); } while (0)
; #define PG8_LDB(dst, b, h) do { _Pragma("unroll") for (int n = 0; n < 2; ++n) _Pragma("unroll") for (int k = 0; k < 2; ++k) dst[n][k] = *(const LAS bf16x8*)(lds + PG8_SB(b, h) + boff + n * 2048 + k * 1024); } while (0)
; #define PG8_MMA(ai, bj, At, Bt) do { __builtin_amdgcn_s_setprio(1); _Pragma("unroll") for (int m = 0; m < 4; ++m) _Pragma("unroll") for (int n = 0; n < 2; ++n) _Pragma("unroll") for (int k = 0; k < 2; ++k) \
;         acc[ai][bj][m][n] = __builtin_amdgcn_mfma_f32_16x16x32_bf16(Bt[n][k], At[m][k], acc[ai][bj][m][n], 0, 0, 0); __builtin_amdgcn_s_setprio(0); } while (0)
; #define PG8_WAIT_V(n) asm volatile("s_waitcnt vmcnt(" #n ")" ::: "memory")
; #define PG8_WAIT_L(n) asm volatile("s_waitcnt lgkmcnt(" #n ")" ::: "memory")
; #define PG8_BAR __builtin_amdgcn_s_barrier()
; #define PG8_SCHED __builtin_amdgcn_sched_barrier(0)
; template <class Epi>
; DI void gemm_phase(LAS unsigned char* lds, const Gemm g, const StaticOrder& S, const Epi& E, const int tid) {
;     ...
;             PG8_LDB(B0, 0, 0); PG8_SCHED; PG8_LDA(At, 0, 0); PG8_STAGE(PG8_SA(1, 1), a1 + hstepA, voffA);
;             PG8_WAIT_L(8); PG8_BAR; PG8_WAIT_L(0); PG8_MMA(0, 0, At, B0); PG8_BAR; PG8_SCHED;
;             PG8_LDB(B1, 0, 1); PG8_STAGE(PG8_SB(0, 0), b2, voffB);
;             PG8_BAR; PG8_WAIT_L(0); PG8_MMA(0, 1, At, B1); PG8_BAR;
;             PG8_LDA(At, 0, 1); PG8_STAGE(PG8_SA(0, 0), a2, voffA);
;             PG8_BAR; PG8_WAIT_L(0); PG8_MMA(1, 0, At, B0); PG8_BAR; PG8_SCHED;
;             PG8_STAGE(PG8_SB(0, 1), b2 + hstepB, voffB);
;             PG8_WAIT_V(6); PG8_BAR; PG8_MMA(1, 1, At, B1); PG8_BAR;
.LBB0_62:
	s_add_i32 s69, 0, 0x10000
	ds_read_b128 v[158:161], v241
	ds_read_b128 v[162:165], v241 offset:1024
	ds_read_b128 v[166:169], v241 offset:2048
	ds_read_b128 v[178:181], v241 offset:3072
	s_add_i32 m0, s41, 0xc000
	ds_read_b128 v[182:185], v151
	ds_read_b128 v[186:189], v151 offset:1024
	ds_read_b128 v[190:193], v151 offset:2048
	ds_read_b128 v[194:197], v151 offset:3072
	ds_read_b128 v[198:201], v151 offset:4096
	ds_read_b128 v[202:205], v151 offset:5120
	ds_read_b128 v[206:209], v151 offset:6144
	ds_read_b128 v[210:213], v151 offset:7168
	global_load_lds_dwordx4 v138, s[86:87]
	s_add_i32 m0, s41, 0xe000
	s_nop 0
	global_load_lds_dwordx4 v140, s[86:87]
	s_waitcnt lgkmcnt(8)
	s_barrier
	s_waitcnt lgkmcnt(0)
	s_setprio 1
	s_waitcnt lgkmcnt(0)
	v_mfma_f32_16x16x32_bf16 v[126:129], v[158:161], v[182:185], v[126:129]
	v_mfma_f32_16x16x32_bf16 v[122:125], v[166:169], v[182:185], v[122:125]
	v_mfma_f32_16x16x32_bf16 v[118:121], v[158:161], v[190:193], v[118:121]
	v_mfma_f32_16x16x32_bf16 v[114:117], v[166:169], v[190:193], v[114:117]
	v_mfma_f32_16x16x32_bf16 v[102:105], v[158:161], v[198:201], v[102:105]
	v_mfma_f32_16x16x32_bf16 v[98:101], v[166:169], v[198:201], v[98:101]
	v_mfma_f32_16x16x32_bf16 v[86:89], v[158:161], v[206:209], v[86:89]
	v_mfma_f32_16x16x32_bf16 v[82:85], v[166:169], v[206:209], v[82:85]
	v_mfma_f32_16x16x32_bf16 v[126:129], v[162:165], v[186:189], v[126:129]
	v_mfma_f32_16x16x32_bf16 v[122:125], v[178:181], v[186:189], v[122:125]
	v_mfma_f32_16x16x32_bf16 v[118:121], v[162:165], v[194:197], v[118:121]
	v_mfma_f32_16x16x32_bf16 v[114:117], v[178:181], v[194:197], v[114:117]
	v_mfma_f32_16x16x32_bf16 v[102:105], v[162:165], v[202:205], v[102:105]
	v_mfma_f32_16x16x32_bf16 v[98:101], v[178:181], v[202:205], v[98:101]
	v_mfma_f32_16x16x32_bf16 v[86:89], v[162:165], v[210:213], v[86:89]
	v_mfma_f32_16x16x32_bf16 v[82:85], v[178:181], v[210:213], v[82:85]
	s_setprio 0
	s_barrier
	s_add_i32 s78, 0, 0x14000
	s_add_i32 s69, s69, s26
	ds_read_b128 v[214:217], v242
	ds_read_b128 v[218:221], v242 offset:1024
	ds_read_b128 v[222:225], v242 offset:2048
	ds_read_b128 v[226:229], v242 offset:3072
	s_mov_b32 m0, s69
	s_nop 0
	global_load_lds_dwordx4 v0, s[6:7]
	s_add_i32 m0, s69, 0x2000
	s_nop 0
	global_load_lds_dwordx4 v130, s[6:7]
	s_barrier
	s_waitcnt lgkmcnt(0)
	s_setprio 1
	s_waitcnt lgkmcnt(0)
	v_mfma_f32_16x16x32_bf16 v[110:113], v[214:217], v[182:185], v[110:113]
	v_mfma_f32_16x16x32_bf16 v[106:109], v[222:225], v[182:185], v[106:109]
	v_mfma_f32_16x16x32_bf16 v[94:97], v[214:217], v[190:193], v[94:97]
	v_mfma_f32_16x16x32_bf16 v[90:93], v[222:225], v[190:193], v[90:93]
	v_mfma_f32_16x16x32_bf16 v[78:81], v[214:217], v[198:201], v[78:81]
	v_mfma_f32_16x16x32_bf16 v[74:77], v[222:225], v[198:201], v[74:77]
	v_mfma_f32_16x16x32_bf16 v[70:73], v[214:217], v[206:209], v[70:73]
	v_mfma_f32_16x16x32_bf16 v[66:69], v[222:225], v[206:209], v[66:69]
	v_mfma_f32_16x16x32_bf16 v[110:113], v[218:221], v[186:189], v[110:113]
	v_mfma_f32_16x16x32_bf16 v[106:109], v[226:229], v[186:189], v[106:109]
	v_mfma_f32_16x16x32_bf16 v[94:97], v[218:221], v[194:197], v[94:97]
	v_mfma_f32_16x16x32_bf16 v[90:93], v[226:229], v[194:197], v[90:93]
	v_mfma_f32_16x16x32_bf16 v[78:81], v[218:221], v[202:205], v[78:81]
	v_mfma_f32_16x16x32_bf16 v[74:77], v[226:229], v[202:205], v[74:77]
	v_mfma_f32_16x16x32_bf16 v[70:73], v[218:221], v[210:213], v[70:73]
	v_mfma_f32_16x16x32_bf16 v[66:69], v[226:229], v[210:213], v[66:69]
	s_setprio 0
	s_mov_b32 m0, s41
	s_barrier
	ds_read_b128 v[182:185], v151 offset:16384
	ds_read_b128 v[186:189], v151 offset:17408
	ds_read_b128 v[190:193], v151 offset:18432
	ds_read_b128 v[194:197], v151 offset:19456
	ds_read_b128 v[198:201], v151 offset:20480
	ds_read_b128 v[202:205], v151 offset:21504
	ds_read_b128 v[206:209], v151 offset:22528
	ds_read_b128 v[210:213], v151 offset:23552
	global_load_lds_dwordx4 v134, s[50:51]
	s_mov_b32 m0, s55
	s_nop 0
	global_load_lds_dwordx4 v132, s[50:51]
	s_barrier
	s_waitcnt lgkmcnt(0)
	s_setprio 1
	s_waitcnt lgkmcnt(0)
	v_mfma_f32_16x16x32_bf16 v[62:65], v[158:161], v[182:185], v[62:65]
	v_mfma_f32_16x16x32_bf16 v[58:61], v[166:169], v[182:185], v[58:61]
	v_mfma_f32_16x16x32_bf16 v[54:57], v[158:161], v[190:193], v[54:57]
	v_mfma_f32_16x16x32_bf16 v[50:53], v[166:169], v[190:193], v[50:53]
	v_mfma_f32_16x16x32_bf16 v[38:41], v[158:161], v[198:201], v[38:41]
	v_mfma_f32_16x16x32_bf16 v[34:37], v[166:169], v[198:201], v[34:37]
	v_mfma_f32_16x16x32_bf16 v[22:25], v[158:161], v[206:209], v[22:25]
	v_mfma_f32_16x16x32_bf16 v[18:21], v[166:169], v[206:209], v[18:21]
	v_mfma_f32_16x16x32_bf16 v[62:65], v[162:165], v[186:189], v[62:65]
	v_mfma_f32_16x16x32_bf16 v[58:61], v[178:181], v[186:189], v[58:61]
	v_mfma_f32_16x16x32_bf16 v[54:57], v[162:165], v[194:197], v[54:57]
	v_mfma_f32_16x16x32_bf16 v[50:53], v[178:181], v[194:197], v[50:53]
	v_mfma_f32_16x16x32_bf16 v[38:41], v[162:165], v[202:205], v[38:41]
	v_mfma_f32_16x16x32_bf16 v[34:37], v[178:181], v[202:205], v[34:37]
	v_mfma_f32_16x16x32_bf16 v[22:25], v[162:165], v[210:213], v[22:25]
	v_mfma_f32_16x16x32_bf16 v[18:21], v[178:181], v[210:213], v[18:21]
	s_setprio 0
	s_barrier
	s_add_u32 s86, s6, 0x80000
	s_addc_u32 s87, s7, 0
	s_add_i32 s69, s78, s26
	s_mov_b32 m0, s69
	s_nop 0
	global_load_lds_dwordx4 v0, s[86:87]
	s_add_i32 m0, s69, 0x2000
	s_nop 0
	global_load_lds_dwordx4 v130, s[86:87]
	s_waitcnt vmcnt(6)
	s_barrier
; #define PG8_STAGE(bufoff, gbase, voff) do { _Pragma("unroll") for (int _i = 0; _i < 2; ++_i) \
;         __builtin_amdgcn_global_load_lds((const unsigned*)((const char*)(gbase) + (voff)[_i]), (LAS unsigned*)(lds + (bufoff) + ldsw + _i * 8192), 16, 0, 0); } while (0)
; #define PG8_LDA(dst, b, h) do { _Pragma("unroll") for (int m = 0; m < 4; ++m) _Pragma("unroll") for (int k = 0; k < 2; ++k) dst[m][k] = *(const LAS bf16x8*)(lds + PG8_SA(b, h) + aoff + m * 2048 + k * 1024); } while (0)
; #define PG8_LDB(dst, b, h) do { _Pragma("unroll") for (int n = 0; n < 2; ++n) _Pragma("unroll") for (int k = 0; k < 2; ++k) dst[n][k] = *(const LAS bf16x8*)(lds + PG8_SB(b, h) + boff + n * 2048 + k * 1024); } while (0)
; #define PG8_MMA(ai, bj, At, Bt) do { __builtin_amdgcn_s_setprio(1); _Pragma("unroll") for (int m = 0; m < 4; ++m) _Pragma("unroll") for (int n = 0; n < 2; ++n) _Pragma("unroll") for (int k = 0; k < 2; ++k) \
;         acc[ai][bj][m][n] = __builtin_amdgcn_mfma_f32_16x16x32_bf16(Bt[n][k], At[m][k], acc[ai][bj][m][n], 0, 0, 0); __builtin_amdgcn_s_setprio(0); } while (0)
; #define PG8_WAIT_V(n) asm volatile("s_waitcnt vmcnt(" #n ")" ::: "memory")
; #define PG8_WAIT_L(n) asm volatile("s_waitcnt lgkmcnt(" #n ")" ::: "memory")
; #define PG8_BAR __builtin_amdgcn_s_barrier()
; #define PG8_SCHED __builtin_amdgcn_sched_barrier(0)
; template <class Epi>
; DI void gemm_phase(LAS unsigned char* lds, const Gemm g, const StaticOrder& S, const Epi& E, const int tid) {
;     ...
;             PG8_WAIT_V(6); PG8_BAR; PG8_MMA(1, 1, At, B1); PG8_BAR;
;             PG8_LDB(B0, 1, 0); PG8_SCHED; PG8_LDA(At, 1, 0); PG8_STAGE(PG8_SA(0, 1), a2 + hstepA, voffA);
;             PG8_WAIT_L(8); PG8_BAR; PG8_WAIT_L(0); PG8_MMA(0, 0, At, B0); PG8_BAR; PG8_SCHED;
;             PG8_LDB(B1, 1, 1); PG8_STAGE(PG8_SB(1, 0), b3, voffB);
;             PG8_BAR; PG8_WAIT_L(0); PG8_MMA(0, 1, At, B1); PG8_BAR;
;             PG8_LDA(At, 1, 1); PG8_STAGE(PG8_SA(1, 0), a3, voffA);
	s_setprio 1
	v_mfma_f32_16x16x32_bf16 v[46:49], v[214:217], v[182:185], v[46:49]
	v_mfma_f32_16x16x32_bf16 v[42:45], v[222:225], v[182:185], v[42:45]
	v_mfma_f32_16x16x32_bf16 v[30:33], v[214:217], v[190:193], v[30:33]
	v_mfma_f32_16x16x32_bf16 v[26:29], v[222:225], v[190:193], v[26:29]
	v_mfma_f32_16x16x32_bf16 v[14:17], v[214:217], v[198:201], v[14:17]
	v_mfma_f32_16x16x32_bf16 v[10:13], v[222:225], v[198:201], v[10:13]
	v_mfma_f32_16x16x32_bf16 v[6:9], v[214:217], v[206:209], v[6:9]
	v_mfma_f32_16x16x32_bf16 v[2:5], v[222:225], v[206:209], v[2:5]
	v_mfma_f32_16x16x32_bf16 v[46:49], v[218:221], v[186:189], v[46:49]
	v_mfma_f32_16x16x32_bf16 v[42:45], v[226:229], v[186:189], v[42:45]
	v_mfma_f32_16x16x32_bf16 v[30:33], v[218:221], v[194:197], v[30:33]
	v_mfma_f32_16x16x32_bf16 v[26:29], v[226:229], v[194:197], v[26:29]
	v_mfma_f32_16x16x32_bf16 v[14:17], v[218:221], v[202:205], v[14:17]
	v_mfma_f32_16x16x32_bf16 v[10:13], v[226:229], v[202:205], v[10:13]
	v_mfma_f32_16x16x32_bf16 v[6:9], v[218:221], v[210:213], v[6:9]
	v_mfma_f32_16x16x32_bf16 v[2:5], v[226:229], v[210:213], v[2:5]
	s_setprio 0
	s_add_i32 s69, 0, 0x18000
	s_barrier
	ds_read_b128 v[158:161], v243
	ds_read_b128 v[162:165], v243 offset:1024
	ds_read_b128 v[166:169], v243 offset:2048
	ds_read_b128 v[178:181], v243 offset:3072
	s_add_u32 s50, s50, 0x80000
	s_addc_u32 s51, s51, 0
	s_mov_b32 m0, s56
	s_nop 0
	ds_read_b128 v[182:185], v151 offset:32768
	ds_read_b128 v[186:189], v151 offset:33792
	ds_read_b128 v[190:193], v151 offset:34816
	ds_read_b128 v[194:197], v151 offset:35840
	ds_read_b128 v[198:201], v151 offset:36864
	ds_read_b128 v[202:205], v151 offset:37888
	ds_read_b128 v[206:209], v151 offset:38912
	ds_read_b128 v[210:213], v151 offset:39936
	global_load_lds_dwordx4 v134, s[50:51]
	s_mov_b32 m0, s57
	s_nop 0
	global_load_lds_dwordx4 v132, s[50:51]
	s_waitcnt lgkmcnt(8)
	s_barrier
	s_waitcnt lgkmcnt(0)
	s_setprio 1
	s_waitcnt lgkmcnt(0)
	v_mfma_f32_16x16x32_bf16 v[126:129], v[158:161], v[182:185], v[126:129]
	v_mfma_f32_16x16x32_bf16 v[122:125], v[166:169], v[182:185], v[122:125]
	v_mfma_f32_16x16x32_bf16 v[118:121], v[158:161], v[190:193], v[118:121]
	v_mfma_f32_16x16x32_bf16 v[114:117], v[166:169], v[190:193], v[114:117]
	v_mfma_f32_16x16x32_bf16 v[102:105], v[158:161], v[198:201], v[102:105]
	v_mfma_f32_16x16x32_bf16 v[98:101], v[166:169], v[198:201], v[98:101]
	v_mfma_f32_16x16x32_bf16 v[86:89], v[158:161], v[206:209], v[86:89]
	v_mfma_f32_16x16x32_bf16 v[82:85], v[166:169], v[206:209], v[82:85]
	v_mfma_f32_16x16x32_bf16 v[126:129], v[162:165], v[186:189], v[126:129]
	v_mfma_f32_16x16x32_bf16 v[122:125], v[178:181], v[186:189], v[122:125]
	v_mfma_f32_16x16x32_bf16 v[118:121], v[162:165], v[194:197], v[118:121]
	v_mfma_f32_16x16x32_bf16 v[114:117], v[178:181], v[194:197], v[114:117]
	v_mfma_f32_16x16x32_bf16 v[102:105], v[162:165], v[202:205], v[102:105]
	v_mfma_f32_16x16x32_bf16 v[98:101], v[178:181], v[202:205], v[98:101]
	v_mfma_f32_16x16x32_bf16 v[86:89], v[162:165], v[210:213], v[86:89]
	v_mfma_f32_16x16x32_bf16 v[82:85], v[178:181], v[210:213], v[82:85]
	s_setprio 0
	s_barrier
	s_add_i32 s50, 0, 0x1c000
	s_add_i32 s51, s69, s26
	s_add_u32 s86, s6, s84
	s_addc_u32 s87, s7, s85
	s_mov_b32 m0, s51
	ds_read_b128 v[214:217], v244
	ds_read_b128 v[218:221], v244 offset:1024
	ds_read_b128 v[222:225], v244 offset:2048
	ds_read_b128 v[226:229], v244 offset:3072
	global_load_lds_dwordx4 v0, s[86:87]
	s_add_i32 m0, s51, 0x2000
	s_nop 0
	global_load_lds_dwordx4 v130, s[86:87]
	s_barrier
	s_waitcnt lgkmcnt(0)
	s_setprio 1
	s_waitcnt lgkmcnt(0)
	v_mfma_f32_16x16x32_bf16 v[110:113], v[214:217], v[182:185], v[110:113]
	v_mfma_f32_16x16x32_bf16 v[106:109], v[222:225], v[182:185], v[106:109]
	v_mfma_f32_16x16x32_bf16 v[94:97], v[214:217], v[190:193], v[94:97]
	v_mfma_f32_16x16x32_bf16 v[90:93], v[222:225], v[190:193], v[90:93]
	v_mfma_f32_16x16x32_bf16 v[78:81], v[214:217], v[198:201], v[78:81]
	v_mfma_f32_16x16x32_bf16 v[74:77], v[222:225], v[198:201], v[74:77]
	v_mfma_f32_16x16x32_bf16 v[70:73], v[214:217], v[206:209], v[70:73]
	v_mfma_f32_16x16x32_bf16 v[66:69], v[222:225], v[206:209], v[66:69]
	v_mfma_f32_16x16x32_bf16 v[110:113], v[218:221], v[186:189], v[110:113]
	v_mfma_f32_16x16x32_bf16 v[106:109], v[226:229], v[186:189], v[106:109]
	v_mfma_f32_16x16x32_bf16 v[94:97], v[218:221], v[194:197], v[94:97]
	v_mfma_f32_16x16x32_bf16 v[90:93], v[226:229], v[194:197], v[90:93]
	v_mfma_f32_16x16x32_bf16 v[78:81], v[218:221], v[202:205], v[78:81]
	v_mfma_f32_16x16x32_bf16 v[74:77], v[226:229], v[202:205], v[74:77]
	v_mfma_f32_16x16x32_bf16 v[70:73], v[218:221], v[210:213], v[70:73]
	v_mfma_f32_16x16x32_bf16 v[66:69], v[226:229], v[210:213], v[66:69]
	s_setprio 0
	s_mov_b32 m0, s59
	s_nop 0
	s_barrier
	ds_read_b128 v[182:185], v151 offset:49152
	ds_read_b128 v[186:189], v151 offset:50176
	ds_read_b128 v[190:193], v151 offset:51200
	ds_read_b128 v[194:197], v151 offset:52224
	ds_read_b128 v[198:201], v151 offset:53248
	ds_read_b128 v[202:205], v151 offset:54272
	ds_read_b128 v[206:209], v151 offset:55296
	ds_read_b128 v[210:213], v151 offset:56320
	global_load_lds_dwordx4 v134, s[8:9]
	s_mov_b32 m0, s60
	s_nop 0
	global_load_lds_dwordx4 v132, s[8:9]
	s_barrier
; #define PG8_STAGE(bufoff, gbase, voff) do { _Pragma("unroll") for (int _i = 0; _i < 2; ++_i) \
;         __builtin_amdgcn_global_load_lds((const unsigned*)((const char*)(gbase) + (voff)[_i]), (LAS unsigned*)(lds + (bufoff) + ldsw + _i * 8192), 16, 0, 0); } while (0)
; #define PG8_LDA(dst, b, h) do { _Pragma("unroll") for (int m = 0; m < 4; ++m) _Pragma("unroll") for (int k = 0; k < 2; ++k) dst[m][k] = *(const LAS bf16x8*)(lds + PG8_SA(b, h) + aoff + m * 2048 + k * 1024); } while (0)
; #define PG8_LDB(dst, b, h) do { _Pragma("unroll") for (int n = 0; n < 2; ++n) _Pragma("unroll") for (int k = 0; k < 2; ++k) dst[n][k] = *(const LAS bf16x8*)(lds + PG8_SB(b, h) + boff + n * 2048 + k * 1024); } while (0)
; #define PG8_MMA(ai, bj, At, Bt) do { __builtin_amdgcn_s_setprio(1); _Pragma("unroll") for (int m = 0; m < 4; ++m) _Pragma("unroll") for (int n = 0; n < 2; ++n) _Pragma("unroll") for (int k = 0; k < 2; ++k) \
;         acc[ai][bj][m][n] = __builtin_amdgcn_mfma_f32_16x16x32_bf16(Bt[n][k], At[m][k], acc[ai][bj][m][n], 0, 0, 0); __builtin_amdgcn_s_setprio(0); } while (0)
; #define PG8_WAIT_V(n) asm volatile("s_waitcnt vmcnt(" #n ")" ::: "memory")
; #define PG8_WAIT_L(n) asm volatile("s_waitcnt lgkmcnt(" #n ")" ::: "memory")
; #define PG8_BAR __builtin_amdgcn_s_barrier()
; #define PG8_SCHED __builtin_amdgcn_sched_barrier(0)
; template <class Epi>
; DI void gemm_phase(LAS unsigned char* lds, const Gemm g, const StaticOrder& S, const Epi& E, const int tid) {
;     ...
;             const char* a1 = cA + PG8_KTA(t + 1);
;             const char* a2 = last ? nA : cA + PG8_KTA(t + 2); const char* b2 = last ? nB : cB + (size_t)(t + 2) * kstep;
;             const char* a3 = last ? nA + PG8_KTA(1) : cA + PG8_KTA(t + 3); const char* b3 = b2 + kstep;
;             PG8_LDB(B0, 0, 0); PG8_SCHED; PG8_LDA(At, 0, 0); PG8_STAGE(PG8_SA(1, 1), a1 + hstepA, voffA);
;     ...
;             PG8_BAR; PG8_WAIT_L(0); PG8_MMA(1, 0, At, B0); PG8_BAR; PG8_SCHED;
;             PG8_STAGE(PG8_SB(1, 1), b3 + hstepB, voffB);
;             PG8_WAIT_V(6); PG8_BAR; PG8_MMA(1, 1, At, B1); PG8_BAR;
	s_waitcnt lgkmcnt(0)
	s_setprio 1
	s_waitcnt lgkmcnt(0)
	v_mfma_f32_16x16x32_bf16 v[62:65], v[158:161], v[182:185], v[62:65]
	v_mfma_f32_16x16x32_bf16 v[58:61], v[166:169], v[182:185], v[58:61]
	v_mfma_f32_16x16x32_bf16 v[54:57], v[158:161], v[190:193], v[54:57]
	v_mfma_f32_16x16x32_bf16 v[50:53], v[166:169], v[190:193], v[50:53]
	v_mfma_f32_16x16x32_bf16 v[38:41], v[158:161], v[198:201], v[38:41]
	v_mfma_f32_16x16x32_bf16 v[34:37], v[166:169], v[198:201], v[34:37]
	v_mfma_f32_16x16x32_bf16 v[22:25], v[158:161], v[206:209], v[22:25]
	v_mfma_f32_16x16x32_bf16 v[18:21], v[166:169], v[206:209], v[18:21]
	v_mfma_f32_16x16x32_bf16 v[62:65], v[162:165], v[186:189], v[62:65]
	v_mfma_f32_16x16x32_bf16 v[58:61], v[178:181], v[186:189], v[58:61]
	v_mfma_f32_16x16x32_bf16 v[54:57], v[162:165], v[194:197], v[54:57]
	v_mfma_f32_16x16x32_bf16 v[50:53], v[178:181], v[194:197], v[50:53]
	v_mfma_f32_16x16x32_bf16 v[38:41], v[162:165], v[202:205], v[38:41]
	v_mfma_f32_16x16x32_bf16 v[34:37], v[178:181], v[202:205], v[34:37]
	v_mfma_f32_16x16x32_bf16 v[22:25], v[162:165], v[210:213], v[22:25]
	v_mfma_f32_16x16x32_bf16 v[18:21], v[178:181], v[210:213], v[18:21]
	s_setprio 0
	s_barrier
	s_add_u32 s6, s6, 0x80080
	s_addc_u32 s7, s7, 0
	s_add_i32 s8, s50, s26
	s_mov_b32 m0, s8
	s_nop 0
	global_load_lds_dwordx4 v0, s[6:7]
	s_add_i32 m0, s8, 0x2000
	s_nop 0
	global_load_lds_dwordx4 v130, s[6:7]
	s_waitcnt vmcnt(6)
	s_barrier
	s_setprio 1
	v_mfma_f32_16x16x32_bf16 v[46:49], v[214:217], v[182:185], v[46:49]
	v_mfma_f32_16x16x32_bf16 v[42:45], v[222:225], v[182:185], v[42:45]
	v_mfma_f32_16x16x32_bf16 v[30:33], v[214:217], v[190:193], v[30:33]
	v_mfma_f32_16x16x32_bf16 v[26:29], v[222:225], v[190:193], v[26:29]
	v_mfma_f32_16x16x32_bf16 v[14:17], v[214:217], v[198:201], v[14:17]
	v_mfma_f32_16x16x32_bf16 v[10:13], v[222:225], v[198:201], v[10:13]
	v_mfma_f32_16x16x32_bf16 v[6:9], v[214:217], v[206:209], v[6:9]
	v_mfma_f32_16x16x32_bf16 v[2:5], v[222:225], v[206:209], v[2:5]
	v_mfma_f32_16x16x32_bf16 v[46:49], v[218:221], v[186:189], v[46:49]
	v_mfma_f32_16x16x32_bf16 v[42:45], v[226:229], v[186:189], v[42:45]
	v_mfma_f32_16x16x32_bf16 v[30:33], v[218:221], v[194:197], v[30:33]
	v_mfma_f32_16x16x32_bf16 v[26:29], v[226:229], v[194:197], v[26:29]
	v_mfma_f32_16x16x32_bf16 v[14:17], v[218:221], v[202:205], v[14:17]
	v_mfma_f32_16x16x32_bf16 v[10:13], v[226:229], v[202:205], v[10:13]
	v_mfma_f32_16x16x32_bf16 v[6:9], v[218:221], v[210:213], v[6:9]
	v_mfma_f32_16x16x32_bf16 v[2:5], v[226:229], v[210:213], v[2:5]
	s_setprio 0
	s_add_i32 s68, s68, 2
	s_add_u32 s4, s4, 0x100
	s_addc_u32 s5, s5, 0
	s_add_u32 s6, s44, s4
	s_addc_u32 s7, s45, s5
	s_add_u32 s8, s6, 0x100
	s_addc_u32 s9, s7, 0
	s_add_u32 s69, s66, s4
	s_addc_u32 s78, s67, s5
	s_add_u32 s86, s6, 0x180
	s_addc_u32 s87, s7, 0
	s_cmpk_eq_i32 s4, 0xf00
	s_cselect_b32 s51, s30, s9
	s_cselect_b32 s50, s31, s8
	s_cselect_b32 s7, s39, s78
	s_cselect_b32 s6, s43, s69
	s_cselect_b32 s9, s65, s87
	s_cselect_b32 s8, s64, s86
	s_add_u32 s86, s44, s4
	s_addc_u32 s87, s45, s5
	s_add_u32 s86, s86, 0x80080
	s_addc_u32 s87, s87, 0
	s_cmp_gt_u32 s68, 29
	s_barrier
	s_cbranch_scc0 .LBB0_62
	s_and_b64 vcc, exec, s[34:35]
	s_cbranch_vccnz .Lp1_skip
	s_add_u32 s86, s46, 0x80080
	s_addc_u32 s87, s47, 0
	s_add_i32 m0, s41, 0xc000
	s_nop 0
	global_load_lds_dwordx4 v138, s[86:87]
	s_add_i32 m0, s41, 0xe000
	s_nop 0
	global_load_lds_dwordx4 v140, s[86:87]
	s_mov_b32 s101, 1
; DI unsigned pk2(float a, float b) { f32x2 v = {a, b}; bf16v2 r = __builtin_convertvector(v, bf16v2); return __builtin_bit_cast(unsigned, r); }
;     DI void operator()(const f32x4 (&acc)[2][2][4][2], const Unit& u, int wr, int wc, int fr, int fq) const {
;     ...
;             unsigned char* tb = (unsigned char*)O + ((size_t)(u.pm * nt + u.pn) << 17) + (wr * 4 + wc) * 1024 + (fq * 16 + fr) * 16;
; #pragma unroll
;             for (int ai = 0; ai < 2; ++ai)
; #pragma unroll
;                 for (int m = 0; m < 4; ++m)
; #pragma unroll
;                     for (int bj = 0; bj < 2; ++bj) { const f32x4 v0 = acc[ai][bj][m][0], v1 = acc[ai][bj][m][1];
;                         u32x4 w; w.x = pk2(v0[0], v0[1]); w.y = pk2(v0[2], v0[3]); w.z = pk2(v1[0], v1[1]); w.w = pk2(v1[2], v1[3]);
;                         *(u32x4*)(tb + ((ai * 4 + m) * 2 + bj) * 8192) = w; }
; template <class Epi>
; DI void gemm_phase(LAS unsigned char* lds, const Gemm g, const StaticOrder& S, const Epi& E, const int tid) {
;     ...
;         E(acc, cur, wr, wc, fr, fq);
;         if (!has_next) break;
.Lp1_skip:
	s_mul_i32 s4, s40, s58
	s_add_i32 s4, s4, s63
	s_ashr_i32 s5, s4, 31
	s_lshl_b64 s[4:5], s[4:5], 17
	v_lshl_add_u64 v[144:145], v[136:137], 0, s[4:5]
	s_movk_i32 s4, 0x2000
	v_cvt_pk_bf16_f32 v110, v110, v111
	v_cvt_pk_bf16_f32 v111, v112, v113
	v_cvt_pk_bf16_f32 v112, v106, v107
	v_add_co_u32_e32 v106, vcc, s4, v144
	v_cvt_pk_bf16_f32 v113, v108, v109
	s_nop 0
	v_addc_co_u32_e32 v107, vcc, 0, v145, vcc
	global_store_dwordx4 v[106:107], v[110:113], off
	s_movk_i32 s4, 0x6000
	v_cvt_pk_bf16_f32 v94, v94, v95
	v_add_co_u32_e32 v110, vcc, s3, v144
	v_cvt_pk_bf16_f32 v95, v96, v97
	s_nop 0
	v_addc_co_u32_e32 v111, vcc, 0, v145, vcc
	v_cvt_pk_bf16_f32 v96, v90, v91
	v_add_co_u32_e32 v90, vcc, s4, v144
	v_cvt_pk_bf16_f32 v97, v92, v93
	s_nop 0
	v_addc_co_u32_e32 v91, vcc, 0, v145, vcc
	s_mov_b32 s4, 0x8000
	global_store_dwordx4 v[90:91], v[94:97], off
	v_cvt_pk_bf16_f32 v78, v78, v79
	v_cvt_pk_bf16_f32 v79, v80, v81
	v_add_co_u32_e32 v94, vcc, s4, v144
	s_mov_b32 s4, 0xa000
	s_nop 0
	v_addc_co_u32_e32 v95, vcc, 0, v145, vcc
	v_cvt_pk_bf16_f32 v80, v74, v75
	v_add_co_u32_e32 v74, vcc, s4, v144
	v_cvt_pk_bf16_f32 v81, v76, v77
	s_nop 0
	v_addc_co_u32_e32 v75, vcc, 0, v145, vcc
	global_store_dwordx4 v[74:75], v[78:81], off
	s_mov_b32 s4, 0xe000
	v_cvt_pk_bf16_f32 v70, v70, v71
	v_add_co_u32_e32 v78, vcc, s13, v144
	v_cvt_pk_bf16_f32 v71, v72, v73
	s_nop 0
	v_addc_co_u32_e32 v79, vcc, 0, v145, vcc
	v_cvt_pk_bf16_f32 v72, v66, v67
	v_add_co_u32_e32 v66, vcc, s4, v144
	s_mov_b32 s4, 0x10000
	s_nop 0
	v_addc_co_u32_e32 v67, vcc, 0, v145, vcc
	v_cvt_pk_bf16_f32 v62, v62, v63
	v_cvt_pk_bf16_f32 v63, v64, v65
	v_cvt_pk_bf16_f32 v64, v58, v59
	v_add_co_u32_e32 v58, vcc, s4, v144
	s_mov_b32 s4, 0x12000
	s_nop 0
	v_addc_co_u32_e32 v59, vcc, 0, v145, vcc
	v_cvt_pk_bf16_f32 v46, v46, v47
	v_cvt_pk_bf16_f32 v47, v48, v49
	v_cvt_pk_bf16_f32 v48, v42, v43
	v_add_co_u32_e32 v42, vcc, s4, v144
	v_cvt_pk_bf16_f32 v49, v44, v45
	s_nop 0
	v_addc_co_u32_e32 v43, vcc, 0, v145, vcc
	s_mov_b32 s4, 0x14000
	global_store_dwordx4 v[42:43], v[46:49], off
	v_cvt_pk_bf16_f32 v30, v30, v31
	v_cvt_pk_bf16_f32 v31, v32, v33
	v_add_co_u32_e32 v46, vcc, s4, v144
	s_mov_b32 s4, 0x16000
	s_nop 0
	v_addc_co_u32_e32 v47, vcc, 0, v145, vcc
	v_cvt_pk_bf16_f32 v32, v26, v27
	v_add_co_u32_e32 v26, vcc, s4, v144
	v_cvt_pk_bf16_f32 v33, v28, v29
	s_nop 0
	v_addc_co_u32_e32 v27, vcc, 0, v145, vcc
	s_mov_b32 s4, 0x18000
	global_store_dwordx4 v[26:27], v[30:33], off
	v_cvt_pk_bf16_f32 v14, v14, v15
	v_cvt_pk_bf16_f32 v15, v16, v17
	v_add_co_u32_e32 v30, vcc, s4, v144
	s_mov_b32 s4, 0x1a000
	s_nop 0
	v_addc_co_u32_e32 v31, vcc, 0, v145, vcc
	v_cvt_pk_bf16_f32 v16, v10, v11
	v_add_co_u32_e32 v10, vcc, s4, v144
	v_cvt_pk_bf16_f32 v17, v12, v13
	s_nop 0
	v_addc_co_u32_e32 v11, vcc, 0, v145, vcc
	s_mov_b32 s4, 0x1c000
	global_store_dwordx4 v[10:11], v[14:17], off
	v_cvt_pk_bf16_f32 v6, v6, v7
	v_cvt_pk_bf16_f32 v7, v8, v9
	v_add_co_u32_e32 v14, vcc, s4, v144
	v_cvt_pk_bf16_f32 v8, v2, v3
	s_nop 0
	v_addc_co_u32_e32 v15, vcc, 0, v145, vcc
	v_add_co_u32_e32 v2, vcc, 0x1e000, v144
	v_cvt_pk_bf16_f32 v126, v126, v127
	s_nop 0
	v_addc_co_u32_e32 v3, vcc, 0, v145, vcc
	v_cvt_pk_bf16_f32 v127, v128, v129
	v_cvt_pk_bf16_f32 v128, v122, v123
	v_cvt_pk_bf16_f32 v129, v124, v125
	v_cvt_pk_bf16_f32 v106, v118, v119
	v_cvt_pk_bf16_f32 v107, v120, v121
	v_cvt_pk_bf16_f32 v108, v114, v115
	v_cvt_pk_bf16_f32 v109, v116, v117
	v_cvt_pk_bf16_f32 v90, v102, v103
	v_cvt_pk_bf16_f32 v91, v104, v105
	v_cvt_pk_bf16_f32 v92, v98, v99
	v_cvt_pk_bf16_f32 v93, v100, v101
	v_cvt_pk_bf16_f32 v74, v86, v87
	v_cvt_pk_bf16_f32 v75, v88, v89
	v_cvt_pk_bf16_f32 v76, v82, v83
	v_cvt_pk_bf16_f32 v77, v84, v85
	v_cvt_pk_bf16_f32 v73, v68, v69
	v_cvt_pk_bf16_f32 v65, v60, v61
	v_cvt_pk_bf16_f32 v42, v54, v55
	v_cvt_pk_bf16_f32 v43, v56, v57
	v_cvt_pk_bf16_f32 v44, v50, v51
	v_cvt_pk_bf16_f32 v45, v52, v53
	v_cvt_pk_bf16_f32 v26, v38, v39
	v_cvt_pk_bf16_f32 v27, v40, v41
	v_cvt_pk_bf16_f32 v28, v34, v35
	v_cvt_pk_bf16_f32 v29, v36, v37
	v_cvt_pk_bf16_f32 v10, v22, v23
	v_cvt_pk_bf16_f32 v11, v24, v25
	v_cvt_pk_bf16_f32 v12, v18, v19
	v_cvt_pk_bf16_f32 v13, v20, v21
	v_cvt_pk_bf16_f32 v9, v4, v5
	s_and_b64 vcc, exec, s[34:35]
	s_mov_b32 s63, s38
	s_mov_b32 s40, s42
	s_mov_b64 s[4:5], s[48:49]
	s_mov_b64 s[44:45], s[46:47]
	global_store_dwordx4 v[144:145], v[126:129], off
	global_store_dwordx4 v[110:111], v[106:109], off
	global_store_dwordx4 v[94:95], v[90:93], off
	global_store_dwordx4 v[78:79], v[74:77], off
	global_store_dwordx4 v[66:67], v[70:73], off
	global_store_dwordx4 v[58:59], v[62:65], off
	global_store_dwordx4 v[46:47], v[42:45], off
	global_store_dwordx4 v[30:31], v[26:29], off
	global_store_dwordx4 v[14:15], v[10:13], off
	global_store_dwordx4 v[2:3], v[6:9], off
	s_cbranch_vccz .LBB0_59
	s_waitcnt vmcnt(0)
	s_cmpk_gt_u32 s25, 0xff
	s_cbranch_scc1 .LBB0_66
	s_barrier
